# attention: K LDS-DMA after the fourth QK MFMA pair (all K fragment reads issued first)
# baseline (speedup 1.0000x reference)
; #define SBAR() __builtin_amdgcn_sched_barrier(0)
; #define KRD(A, B, d0) do { const int ad_ = (kc ^ ((d0) << 5)) + kbt; A = lds_rd128<0>(ad_); B = lds_rd128<8192>(ad_); } while (0)
; __device__ __forceinline__ float softmax_rel(f32x16& p0, f32x16& p1, bool first, float& m_reg, float& l_reg, bf16x8& pa0, bf16x8& pa1, bf16x8& pa2, bf16x8& pa3) {
;   float pmax = p0[0];
; #pragma unroll
;   for (int r = 1; r < 16; ++r) pmax = fmaxf(pmax, p0[r]);
; #pragma unroll
;   for (int r = 0; r < 16; ++r) pmax = fmaxf(pmax, p1[r]);
;   { auto rr = __builtin_amdgcn_permlane32_swap(__float_as_uint(pmax), __float_as_uint(pmax), false, false);
;     pmax = fmaxf(__uint_as_float(rr[0]), __uint_as_float(rr[1])); }
;   float alpha = 1.f;
;   if (__builtin_expect(first || __any(pmax > THR2), 0)) {
; __device__ __forceinline__ void qkt_pipe(f32x16& p0, f32x16& p1, int kbt, int kc, const bf16x8* qr, const f32x16& z) {
;   bf16x8 a0, b0, a1, b1, a2, b2, a3, b3;
;     ...
;   KRD(a0, b0, 0); KRD(a1, b1, 1); KRD(a2, b2, 2); KRD(a3, b3, 3);
;   KW(6); p0 = __builtin_amdgcn_mfma_f32_32x32x16_bf16(a0, qr[0], z, 0, 0, 0);  p1 = __builtin_amdgcn_mfma_f32_32x32x16_bf16(b0, qr[0], z, 0, 0, 0);  SBAR(); KRD(a0, b0, 4);
;   KW(6); p0 = __builtin_amdgcn_mfma_f32_32x32x16_bf16(a1, qr[1], p0, 0, 0, 0); p1 = __builtin_amdgcn_mfma_f32_32x32x16_bf16(b1, qr[1], p1, 0, 0, 0); SBAR(); KRD(a1, b1, 5);
;   KW(6); p0 = __builtin_amdgcn_mfma_f32_32x32x16_bf16(a2, qr[2], p0, 0, 0, 0); p1 = __builtin_amdgcn_mfma_f32_32x32x16_bf16(b2, qr[2], p1, 0, 0, 0); SBAR(); KRD(a2, b2, 6);
;   KW(6); p0 = __builtin_amdgcn_mfma_f32_32x32x16_bf16(a3, qr[3], p0, 0, 0, 0); p1 = __builtin_amdgcn_mfma_f32_32x32x16_bf16(b3, qr[3], p1, 0, 0, 0); SBAR(); KRD(a3, b3, 7);
;   KW(6); p0 = __builtin_amdgcn_mfma_f32_32x32x16_bf16(a0, qr[4], p0, 0, 0, 0); p1 = __builtin_amdgcn_mfma_f32_32x32x16_bf16(b0, qr[4], p1, 0, 0, 0); SBAR();
;   KW(4); p0 = __builtin_amdgcn_mfma_f32_32x32x16_bf16(a1, qr[5], p0, 0, 0, 0); p1 = __builtin_amdgcn_mfma_f32_32x32x16_bf16(b1, qr[5], p1, 0, 0, 0); SBAR();
;   KW(2); p0 = __builtin_amdgcn_mfma_f32_32x32x16_bf16(a2, qr[6], p0, 0, 0, 0); p1 = __builtin_amdgcn_mfma_f32_32x32x16_bf16(b2, qr[6], p1, 0, 0, 0); SBAR();
;   KW(0); p0 = __builtin_amdgcn_mfma_f32_32x32x16_bf16(a3, qr[7], p0, 0, 0, 0); p1 = __builtin_amdgcn_mfma_f32_32x32x16_bf16(b3, qr[7], p1, 0, 0, 0);
.LBB0_348:
	s_mov_b32 s11, s24
	s_setprio 2
	v_lshl_add_u32 v212, s11, 14, v199
	v_add_u32_e32 v144, v212, v213
	ds_read_b128 v[194:197], v144 offset:0
	ds_read_b128 v[226:229], v144 offset:0x2000
	v_xor_b32_e32 v144, 32, v213
	v_add_u32_e32 v144, v212, v144
	ds_read_b128 v[230:233], v144 offset:0
	ds_read_b128 v[234:237], v144 offset:0x2000
	v_xor_b32_e32 v144, 64, v213
	v_add_u32_e32 v144, v212, v144
	ds_read_b128 v[238:241], v144 offset:0
	ds_read_b128 v[242:245], v144 offset:0x2000
	v_xor_b32_e32 v144, 0x60, v213
	v_add_u32_e32 v144, v212, v144
	ds_read_b128 v[246:249], v144 offset:0
	ds_read_b128 v[214:217], v144 offset:0x2000
	s_add_i32 s12, s10, 2
	s_cmp_lt_u32 s12, s74
	s_cselect_b64 s[56:57], -1, 0
	s_cmp_ge_u32 s12, s74
	s_cselect_b64 s[90:91], -1, 0
	s_and_b64 vcc, exec, s[90:91]
	v_xor_b32_e32 v128, 0x80000000, v224
	v_mov_b32_e32 v129, v128
	v_mov_b32_e32 v130, v128
	v_mov_b32_e32 v131, v128
	v_mov_b32_e32 v132, v128
	v_mov_b32_e32 v133, v128
	v_mov_b32_e32 v134, v128
	v_mov_b32_e32 v135, v128
	v_mov_b32_e32 v136, v128
	v_mov_b32_e32 v137, v128
	v_mov_b32_e32 v138, v128
	v_mov_b32_e32 v139, v128
	v_mov_b32_e32 v140, v128
	v_mov_b32_e32 v141, v128
	v_mov_b32_e32 v142, v128
	v_mov_b32_e32 v143, v128
	s_waitcnt lgkmcnt(6)
	s_nop 1
	v_mfma_f32_32x32x16_bf16 v[144:159], v[194:197], v[188:191], v[128:143]
	v_mfma_f32_32x32x16_bf16 v[128:143], v[226:229], v[188:191], v[128:143]
	v_xor_b32_e32 v194, 0x80, v213
	v_add_u32_e32 v220, v212, v194
	ds_read_b128 v[194:197], v220 offset:0
	ds_read_b128 v[226:229], v220 offset:0x2000
	s_waitcnt lgkmcnt(6)
	v_mfma_f32_32x32x16_bf16 v[144:159], v[230:233], v[184:187], v[144:159]
	v_mfma_f32_32x32x16_bf16 v[128:143], v[234:237], v[184:187], v[128:143]
	v_xor_b32_e32 v220, 0xa0, v213
	v_add_u32_e32 v220, v212, v220
	ds_read_b128 v[230:233], v220 offset:0
	ds_read_b128 v[234:237], v220 offset:0x2000
	s_waitcnt lgkmcnt(6)
	v_mfma_f32_32x32x16_bf16 v[144:159], v[238:241], v[180:183], v[144:159]
	v_mfma_f32_32x32x16_bf16 v[128:143], v[242:245], v[180:183], v[128:143]
	v_xor_b32_e32 v220, 0xc0, v213
	v_add_u32_e32 v220, v212, v220
	ds_read_b128 v[238:241], v220 offset:0
	ds_read_b128 v[242:245], v220 offset:0x2000
	s_waitcnt lgkmcnt(6)
	v_mfma_f32_32x32x16_bf16 v[144:159], v[246:249], v[176:179], v[144:159]
	v_mfma_f32_32x32x16_bf16 v[128:143], v[214:217], v[176:179], v[128:143]
	v_xor_b32_e32 v214, 0xe0, v213
	v_add_u32_e32 v212, v212, v214
	ds_read_b128 v[214:217], v212 offset:0
	ds_read_b128 v[246:249], v212 offset:0x2000
	s_cbranch_vccnz .Lq0_nodma
	s_add_u32 s24, s38, 0xfffff000
	s_addc_u32 s25, s39, -1
	s_lshl_b32 s12, s9, 14
	s_add_i32 s12, s12, s0
	s_mov_b32 s13, m0
	s_mov_b32 m0, s12
	s_nop 0
	global_load_lds_dwordx4 v192, s[24:25]
	s_addk_i32 s12, 0x400
	s_mov_b32 m0, s12
	s_nop 0
	global_load_lds_dwordx4 v202, s[24:25]
	s_mov_b32 m0, s13
.Lq0_nodma:
	s_waitcnt lgkmcnt(6)
	v_mfma_f32_32x32x16_bf16 v[144:159], v[194:197], v[172:175], v[144:159]
	v_mfma_f32_32x32x16_bf16 v[128:143], v[226:229], v[172:175], v[128:143]
	s_waitcnt lgkmcnt(4)
	v_mfma_f32_32x32x16_bf16 v[144:159], v[230:233], v[168:171], v[144:159]
	v_mfma_f32_32x32x16_bf16 v[128:143], v[234:237], v[168:171], v[128:143]
	s_waitcnt lgkmcnt(2)
	v_mfma_f32_32x32x16_bf16 v[144:159], v[238:241], v[164:167], v[144:159]
	v_mfma_f32_32x32x16_bf16 v[128:143], v[242:245], v[164:167], v[128:143]
	s_waitcnt lgkmcnt(0)
	v_mfma_f32_32x32x16_bf16 v[144:159], v[214:217], v[160:163], v[144:159]
	s_cmp_eq_u32 s10, 0
	s_cselect_b64 s[62:63], -1, 0
	s_cmp_lg_u32 s10, 0
	v_mfma_f32_32x32x16_bf16 v[128:143], v[246:249], v[160:163], v[128:143]
	s_nop 7
	v_max_f32_e32 v194, v145, v145
	v_max_f32_e32 v195, v144, v144
	v_max_f32_e32 v194, v195, v194
	v_max3_f32 v194, v194, v146, v147
	v_max3_f32 v194, v194, v148, v149
	v_max3_f32 v195, v128, v129, v130
	v_max3_f32 v194, v194, v150, v151
	v_max3_f32 v195, v195, v131, v132
	v_max3_f32 v194, v194, v152, v153
	v_max3_f32 v195, v195, v133, v134
	v_max3_f32 v194, v194, v154, v155
	v_max3_f32 v195, v195, v135, v136
	v_max3_f32 v194, v194, v156, v157
	v_max3_f32 v195, v195, v137, v138
	v_max3_f32 v194, v194, v158, v159
	v_max3_f32 v195, v195, v139, v140
	v_max3_f32 v195, v195, v141, v142
	v_max3_f32 v194, v194, v195, v143
	v_mov_b32_e32 v195, v194
	s_nop 1
	v_permlane32_swap_b32_e32 v194, v195
	v_max_f32_e32 v195, v195, v195
	v_max_f32_e32 v194, v194, v194
	v_max_f32_e32 v226, v194, v195
	s_cbranch_scc0 .LBB0_371
	v_cmp_lt_f32_e32 vcc, s30, v226
	s_cbranch_vccnz .Lm0_rare
	v_mov_b32_e32 v226, 1.0

; #define SBAR() __builtin_amdgcn_sched_barrier(0)
; #define KRD(A, B, d0) do { const int ad_ = (kc ^ ((d0) << 5)) + kbt; A = lds_rd128<0>(ad_); B = lds_rd128<8192>(ad_); } while (0)
; __device__ __forceinline__ float softmax_rel(f32x16& p0, f32x16& p1, bool first, float& m_reg, float& l_reg, bf16x8& pa0, bf16x8& pa1, bf16x8& pa2, bf16x8& pa3) {
;   float pmax = p0[0];
; #pragma unroll
;   for (int r = 1; r < 16; ++r) pmax = fmaxf(pmax, p0[r]);
; #pragma unroll
;   for (int r = 0; r < 16; ++r) pmax = fmaxf(pmax, p1[r]);
;   { auto rr = __builtin_amdgcn_permlane32_swap(__float_as_uint(pmax), __float_as_uint(pmax), false, false);
;     pmax = fmaxf(__uint_as_float(rr[0]), __uint_as_float(rr[1])); }
;   float alpha = 1.f;
;   if (__builtin_expect(first || __any(pmax > THR2), 0)) {
; __device__ __forceinline__ void qkt_pipe(f32x16& p0, f32x16& p1, int kbt, int kc, const bf16x8* qr, const f32x16& z) {
;   bf16x8 a0, b0, a1, b1, a2, b2, a3, b3;
;     ...
;   KRD(a0, b0, 0); KRD(a1, b1, 1); KRD(a2, b2, 2); KRD(a3, b3, 3);
;   KW(6); p0 = __builtin_amdgcn_mfma_f32_32x32x16_bf16(a0, qr[0], z, 0, 0, 0);  p1 = __builtin_amdgcn_mfma_f32_32x32x16_bf16(b0, qr[0], z, 0, 0, 0);  SBAR(); KRD(a0, b0, 4);
;   KW(6); p0 = __builtin_amdgcn_mfma_f32_32x32x16_bf16(a1, qr[1], p0, 0, 0, 0); p1 = __builtin_amdgcn_mfma_f32_32x32x16_bf16(b1, qr[1], p1, 0, 0, 0); SBAR(); KRD(a1, b1, 5);
;   KW(6); p0 = __builtin_amdgcn_mfma_f32_32x32x16_bf16(a2, qr[2], p0, 0, 0, 0); p1 = __builtin_amdgcn_mfma_f32_32x32x16_bf16(b2, qr[2], p1, 0, 0, 0); SBAR(); KRD(a2, b2, 6);
;   KW(6); p0 = __builtin_amdgcn_mfma_f32_32x32x16_bf16(a3, qr[3], p0, 0, 0, 0); p1 = __builtin_amdgcn_mfma_f32_32x32x16_bf16(b3, qr[3], p1, 0, 0, 0); SBAR(); KRD(a3, b3, 7);
;   KW(6); p0 = __builtin_amdgcn_mfma_f32_32x32x16_bf16(a0, qr[4], p0, 0, 0, 0); p1 = __builtin_amdgcn_mfma_f32_32x32x16_bf16(b0, qr[4], p1, 0, 0, 0); SBAR();
;   KW(4); p0 = __builtin_amdgcn_mfma_f32_32x32x16_bf16(a1, qr[5], p0, 0, 0, 0); p1 = __builtin_amdgcn_mfma_f32_32x32x16_bf16(b1, qr[5], p1, 0, 0, 0); SBAR();
;   KW(2); p0 = __builtin_amdgcn_mfma_f32_32x32x16_bf16(a2, qr[6], p0, 0, 0, 0); p1 = __builtin_amdgcn_mfma_f32_32x32x16_bf16(b2, qr[6], p1, 0, 0, 0); SBAR();
;   KW(0); p0 = __builtin_amdgcn_mfma_f32_32x32x16_bf16(a3, qr[7], p0, 0, 0, 0); p1 = __builtin_amdgcn_mfma_f32_32x32x16_bf16(b3, qr[7], p1, 0, 0, 0);
.LBB0_381:
	s_mov_b32 s10, s11
	s_setprio 2
	v_lshl_add_u32 v212, s10, 14, v201
	v_add_u32_e32 v144, v212, v225
	ds_read_b128 v[194:197], v144 offset:0
	ds_read_b128 v[214:217], v144 offset:0x2000
	v_xor_b32_e32 v144, 32, v225
	v_add_u32_e32 v144, v212, v144
	ds_read_b128 v[230:233], v144 offset:0
	ds_read_b128 v[234:237], v144 offset:0x2000
	v_xor_b32_e32 v144, 64, v225
	v_add_u32_e32 v144, v212, v144
	ds_read_b128 v[238:241], v144 offset:0
	ds_read_b128 v[242:245], v144 offset:0x2000
	v_xor_b32_e32 v144, 0x60, v225
	v_add_u32_e32 v144, v212, v144
	ds_read_b128 v[246:249], v144 offset:0
	ds_read_b128 v[220:223], v144 offset:0x2000
	s_add_i32 s11, s9, 2
	s_cmp_lt_u32 s11, s74
	s_cselect_b64 s[52:53], -1, 0
	s_cmp_ge_u32 s11, s74
	s_cselect_b64 s[50:51], -1, 0
	s_and_b64 vcc, exec, s[50:51]
	v_xor_b32_e32 v128, 0x80000000, v227
	v_mov_b32_e32 v129, v128
	v_mov_b32_e32 v130, v128
	v_mov_b32_e32 v131, v128
	v_mov_b32_e32 v132, v128
	v_mov_b32_e32 v133, v128
	v_mov_b32_e32 v134, v128
	v_mov_b32_e32 v135, v128
	v_mov_b32_e32 v136, v128
	v_mov_b32_e32 v137, v128
	v_mov_b32_e32 v138, v128
	v_mov_b32_e32 v139, v128
	v_mov_b32_e32 v140, v128
	v_mov_b32_e32 v141, v128
	v_mov_b32_e32 v142, v128
	v_mov_b32_e32 v143, v128
	s_waitcnt lgkmcnt(6)
	s_nop 1
	v_mfma_f32_32x32x16_bf16 v[144:159], v[194:197], v[188:191], v[128:143]
	v_mfma_f32_32x32x16_bf16 v[128:143], v[214:217], v[188:191], v[128:143]
	v_xor_b32_e32 v194, 0x80, v225
	v_add_u32_e32 v229, v212, v194
	ds_read_b128 v[194:197], v229 offset:0
	ds_read_b128 v[214:217], v229 offset:0x2000
	s_waitcnt lgkmcnt(6)
	v_mfma_f32_32x32x16_bf16 v[144:159], v[230:233], v[184:187], v[144:159]
	v_mfma_f32_32x32x16_bf16 v[128:143], v[234:237], v[184:187], v[128:143]
	v_xor_b32_e32 v229, 0xa0, v225
	v_add_u32_e32 v229, v212, v229
	ds_read_b128 v[230:233], v229 offset:0
	ds_read_b128 v[234:237], v229 offset:0x2000
	s_waitcnt lgkmcnt(6)
	v_mfma_f32_32x32x16_bf16 v[144:159], v[238:241], v[180:183], v[144:159]
	v_mfma_f32_32x32x16_bf16 v[128:143], v[242:245], v[180:183], v[128:143]
	v_xor_b32_e32 v229, 0xc0, v225
	v_add_u32_e32 v229, v212, v229
	ds_read_b128 v[238:241], v229 offset:0
	ds_read_b128 v[242:245], v229 offset:0x2000
	s_waitcnt lgkmcnt(6)
	v_mfma_f32_32x32x16_bf16 v[144:159], v[246:249], v[176:179], v[144:159]
	v_mfma_f32_32x32x16_bf16 v[128:143], v[220:223], v[176:179], v[128:143]
	v_xor_b32_e32 v220, 0xe0, v225
	v_add_u32_e32 v212, v212, v220
	ds_read_b128 v[220:223], v212 offset:0
	ds_read_b128 v[246:249], v212 offset:0x2000
	s_cbranch_vccnz .Lq1_nodma
	s_add_u32 s24, s60, 0xfffff100
	s_addc_u32 s25, s61, -1
	s_lshl_b32 s11, s7, 14
	s_add_i32 s11, s11, s0
	s_mov_b32 s12, m0
	s_mov_b32 m0, s11
	s_nop 0
	global_load_lds_dwordx4 v192, s[24:25]
	s_addk_i32 s11, 0x400
	s_mov_b32 m0, s11
	s_nop 0
	global_load_lds_dwordx4 v202, s[24:25]
	s_mov_b32 m0, s12
.Lq1_nodma:
	s_waitcnt lgkmcnt(6)
	v_mfma_f32_32x32x16_bf16 v[144:159], v[194:197], v[172:175], v[144:159]
	v_mfma_f32_32x32x16_bf16 v[128:143], v[214:217], v[172:175], v[128:143]
	s_waitcnt lgkmcnt(4)
	v_mfma_f32_32x32x16_bf16 v[144:159], v[230:233], v[168:171], v[144:159]
	v_mfma_f32_32x32x16_bf16 v[128:143], v[234:237], v[168:171], v[128:143]
	s_waitcnt lgkmcnt(2)
	v_mfma_f32_32x32x16_bf16 v[144:159], v[238:241], v[164:167], v[144:159]
	v_mfma_f32_32x32x16_bf16 v[128:143], v[242:245], v[164:167], v[128:143]
	s_waitcnt lgkmcnt(0)
	v_mfma_f32_32x32x16_bf16 v[144:159], v[220:223], v[160:163], v[144:159]
	s_cmp_eq_u32 s9, 0
	s_cselect_b64 s[56:57], -1, 0
	s_cmp_lg_u32 s9, 0
	v_mfma_f32_32x32x16_bf16 v[128:143], v[246:249], v[160:163], v[128:143]
	s_nop 7
	v_max_f32_e32 v194, v145, v145
	v_max_f32_e32 v195, v144, v144
	v_max_f32_e32 v194, v195, v194
	v_max3_f32 v194, v194, v146, v147
	v_max3_f32 v194, v194, v148, v149
	v_max3_f32 v195, v128, v129, v130
	v_max3_f32 v194, v194, v150, v151
	v_max3_f32 v195, v195, v131, v132
	v_max3_f32 v194, v194, v152, v153
	v_max3_f32 v195, v195, v133, v134
	v_max3_f32 v194, v194, v154, v155
	v_max3_f32 v195, v195, v135, v136
	v_max3_f32 v194, v194, v156, v157
	v_max3_f32 v195, v195, v137, v138
	v_max3_f32 v194, v194, v158, v159
	v_max3_f32 v195, v195, v139, v140
	v_max3_f32 v195, v195, v141, v142
	v_max3_f32 v194, v194, v195, v143
	v_mov_b32_e32 v195, v194
	s_nop 1
	v_permlane32_swap_b32_e32 v194, v195
	v_max_f32_e32 v195, v195, v195
	v_max_f32_e32 v194, v194, v194
	v_max_f32_e32 v229, v194, v195
	s_cbranch_scc0 .LBB0_404
	v_cmp_lt_f32_e32 vcc, s30, v229
	s_cbranch_vccnz .Lm1_rare
	v_mov_b32_e32 v229, 1.0
